# gla_prep cols tile loads marked nt (read exactly once)
# speedup vs baseline: 1.2283x; 1.0048x over previous
; DEVINL float bf2f(u16 h) { return __uint_as_float(((unsigned)h) << 16); }
; DEVINL float logsig(float z) { return fminf(z, 0.f) - __logf(1.f + __expf(-fabsf(z))); }
; DEVINL int fragpos(int idx) { const int w = idx & 31; return (idx & ~31) + (((w & 15) >> 2) << 3) + (w & 3) + ((w >> 4) << 2); }
; DEVINL void gla_prep_unit(const Params& p, int unit) {
;     ...
;   for (int i = tid; i < 64 * 32; i += 512) {
;     int r = i >> 5, cc = i & 31;
;     afab[i] = bf2f(cols[(tok0 + r) * NCP + C_AF + cc]);
;   }
;   __syncthreads();
;   if (tid < 256) {
;     const int dir = tid >> 7, kk = tid & 127;
;     const float* up = dir ? p.gla_a_up_b : p.gla_a_up_f;
;     const float bias = (dir ? p.gla_a_bias_b : p.gla_a_bias_f)[h * 128 + kk];
;     float u[16];
; #pragma unroll
;     for (int r = 0; r < 16; ++r) u[r] = up[r * 512 + h * 128 + kk];
;     float* Gc = G + dir * 64 * 128 + kk;
;     for (int i = 0; i < 64; ++i) {
;       float z = bias;
; #pragma unroll
;       for (int r = 0; r < 16; ++r) z += afab[i * 32 + dir * 16 + r] * u[r];
;       Gc[i * 128] = logsig(z) * (1.f / 16.f);
;     ...
; #pragma unroll 8
;   for (int idx = tid; idx < 64 * 256; idx += 512) {
;     int i = idx >> 8, vc = idx & 255;
;     VL[vc * 72 + fragpos(i)] = cols[(tok0 + i) * NCP + C_V + h * 256 + vc];
;   }
;   __syncthreads();
;   for (int pc = tid; pc < 4096; pc += 512) {
;     int row = pc >> 3, ch = pc & 7;
;     if (row < 256) {
;       int dir = row >> 7, kk = row & 127;
;       uint4 v = *(const uint4*)(KD + row * 72 + ch * 8);
;       long hb = ((long)(dir * 2 + b) * 4 + h);
;       *(uint4*)((u16*)(ws + O_KDT) + ((hb * 64 + c) * 128 + kk) * 64 + ch * 8) = v;
;     } else {
;       int vc = row - 256;
;       uint4 v = *(const uint4*)(VL + vc * 72 + ch * 8);
;       long hb = ((long)b * 4 + h);
;       *(uint4*)((u16*)(ws + O_VT) + ((hb * 64 + c) * 256 + vc) * 64 + ch * 8) = v;
.Lgl_nofetch:
	s_barrier
	v_mov_b32_e32 v28, 8
	ds_read_b32 v29, v28
	s_waitcnt lgkmcnt(0)
	v_readfirstlane_b32 s3, v29
	s_nop 3
	s_cmp_ge_u32 s3, 0x200
	s_cbranch_scc1 .Lgl_done
	s_and_b32 s41, s3, 3
	s_bfe_u32 s42, s3, 0x60002
	s_lshr_b32 s43, s3, 8
	s_lshl_b32 s44, s43, 12
	s_lshl_b32 s45, s42, 6
	s_add_u32 s44, s44, s45
	s_mul_i32 s44, s44, 0x5400
	s_add_u32 s46, s92, s44
	s_addc_u32 s47, s93, 0
	s_add_u32 s46, s46, 0x4c00000
	s_addc_u32 s47, s47, 0
	global_load_dwordx2 v[82:83], v4, s[46:47] nt
	s_lshl_b32 s48, s41, 8
	s_add_u32 s48, s46, s48
	s_addc_u32 s49, s47, 0
	global_load_dwordx4 v[84:87], v5, s[48:49] nt
	global_load_dwordx4 v[92:95], v5, s[48:49] offset:1024 nt
	s_add_u32 s50, s48, 0xa8000
	s_addc_u32 s51, s49, 0
	global_load_dwordx4 v[88:91], v5, s[50:51] nt
	global_load_dwordx4 v[96:99], v5, s[50:51] offset:1024 nt
	s_lshl_b32 s48, s41, 9
	s_add_u32 s48, s46, s48
	s_addc_u32 s49, s47, 0
	global_load_dwordx4 v[100:103], v6, s[48:49] offset:2048 nt
	s_add_u32 s48, s48, 0x54000
	s_addc_u32 s49, s49, 0
	global_load_dwordx4 v[104:107], v6, s[48:49] offset:2048 nt
	s_add_u32 s48, s48, 0x54000
	s_addc_u32 s49, s49, 0
	global_load_dwordx4 v[108:111], v6, s[48:49] offset:2048 nt
	s_add_u32 s48, s48, 0x54000
	s_addc_u32 s49, s49, 0
	global_load_dwordx4 v[112:115], v6, s[48:49] offset:2048 nt
	s_lshl_b32 s48, s41, 9
	v_add_u32_e32 v24, s48, v7
	global_load_dword v64, v24, s[36:37] offset:0
	global_load_dword v65, v24, s[36:37] offset:2048
	v_add_u32_e32 v24, 0x1000, v24
	global_load_dword v66, v24, s[36:37] offset:0
	global_load_dword v67, v24, s[36:37] offset:2048
	v_add_u32_e32 v24, 0x1000, v24
	global_load_dword v68, v24, s[36:37] offset:0
	global_load_dword v69, v24, s[36:37] offset:2048
	v_add_u32_e32 v24, 0x1000, v24
	global_load_dword v70, v24, s[36:37] offset:0
	global_load_dword v71, v24, s[36:37] offset:2048
	v_add_u32_e32 v24, 0x1000, v24
	global_load_dword v72, v24, s[36:37] offset:0
	global_load_dword v73, v24, s[36:37] offset:2048
	v_add_u32_e32 v24, 0x1000, v24
	global_load_dword v74, v24, s[36:37] offset:0
	global_load_dword v75, v24, s[36:37] offset:2048
	v_add_u32_e32 v24, 0x1000, v24
	global_load_dword v76, v24, s[36:37] offset:0
	global_load_dword v77, v24, s[36:37] offset:2048
	v_add_u32_e32 v24, 0x1000, v24
	global_load_dword v78, v24, s[36:37] offset:0
	global_load_dword v79, v24, s[36:37] offset:2048
	v_add_u32_e32 v25, s48, v7
	global_load_dword v80, v25, s[38:39]
	s_waitcnt vmcnt(25)
	v_lshlrev_b32_e32 v116, 16, v82
	v_and_b32_e32 v117, 0xffff0000, v82
	v_lshlrev_b32_e32 v118, 16, v83
	v_and_b32_e32 v119, 0xffff0000, v83
	ds_write_b128 v2, v[116:119] offset:16
	s_waitcnt vmcnt(21)
	ds_write_b128 v2, v[84:87] offset:8208
	ds_write_b128 v2, v[92:95] offset:24592
	ds_write_b128 v2, v[88:91] offset:16400
	ds_write_b128 v2, v[96:99] offset:32784
	s_waitcnt vmcnt(17)
	v_add_u32_e32 v26, 0x8000, v2
	ds_write_b128 v2, v[100:103] offset:40976
	ds_write_b128 v2, v[104:107] offset:49168
	ds_write_b128 v26, v[108:111] offset:24592
	ds_write_b128 v26, v[112:115] offset:32784
	s_waitcnt lgkmcnt(0)
	s_barrier
	ds_read_u16 v192, v10 offset:0
	ds_read_u16 v193, v10 offset:512
	ds_read_u16 v194, v10 offset:1024
	ds_read_u16 v195, v10 offset:1536
	ds_read_u16 v196, v10 offset:2048
	ds_read_u16 v197, v10 offset:2560
	ds_read_u16 v198, v10 offset:3072
	ds_read_u16 v199, v10 offset:3584
	ds_read_u16 v200, v10 offset:4096
	ds_read_u16 v201, v10 offset:4608
	ds_read_u16 v202, v10 offset:5120
	ds_read_u16 v203, v10 offset:5632
	ds_read_u16 v204, v10 offset:6144
	ds_read_u16 v205, v10 offset:6656
	ds_read_u16 v206, v10 offset:7168
	ds_read_u16 v207, v10 offset:7680
	ds_read_u16 v208, v10 offset:8192
	ds_read_u16 v209, v10 offset:8704
	ds_read_u16 v210, v10 offset:9216
	ds_read_u16 v211, v10 offset:9728
	ds_read_u16 v212, v10 offset:10240
	ds_read_u16 v213, v10 offset:10752
	ds_read_u16 v214, v10 offset:11264
	ds_read_u16 v215, v10 offset:11776
	ds_read_u16 v216, v10 offset:12288
	ds_read_u16 v217, v10 offset:12800
	ds_read_u16 v218, v10 offset:13312
	ds_read_u16 v219, v10 offset:13824
	ds_read_u16 v220, v10 offset:14336
	ds_read_u16 v221, v10 offset:14848
	ds_read_u16 v222, v10 offset:15360
	ds_read_u16 v223, v10 offset:15872
	s_lshl_b32 s48, s43, 2
	s_add_u32 s48, s48, s41
	s_lshl_b32 s48, s48, 6
	s_add_u32 s48, s48, s42
	s_lshl_b32 s48, s48, 15
	s_add_u32 s48, s92, s48
	s_addc_u32 s49, s93, 0
	s_add_u32 s48, s48, 0x1a400000
	s_addc_u32 s49, s49, 0
	s_waitcnt lgkmcnt(0)
	v_lshl_or_b32 v144, v193, 16, v192
	v_lshl_or_b32 v145, v195, 16, v194
	v_lshl_or_b32 v146, v209, 16, v208
	v_lshl_or_b32 v147, v211, 16, v210
	v_lshl_or_b32 v148, v197, 16, v196
	v_lshl_or_b32 v149, v199, 16, v198
	v_lshl_or_b32 v150, v213, 16, v212
	v_lshl_or_b32 v151, v215, 16, v214
	v_lshl_or_b32 v152, v201, 16, v200
	v_lshl_or_b32 v153, v203, 16, v202
	v_lshl_or_b32 v154, v217, 16, v216
	v_lshl_or_b32 v155, v219, 16, v218
	v_lshl_or_b32 v156, v205, 16, v204
	v_lshl_or_b32 v157, v207, 16, v206
	v_lshl_or_b32 v158, v221, 16, v220
	v_lshl_or_b32 v159, v223, 16, v222
	global_store_dwordx4 v11, v[144:147], s[48:49] offset:0
	global_store_dwordx4 v11, v[148:151], s[48:49] offset:16
	global_store_dwordx4 v11, v[152:155], s[48:49] offset:32
	global_store_dwordx4 v11, v[156:159], s[48:49] offset:48
	s_waitcnt vmcnt(4)
	s_mov_b32 s52, 0xbfb8aa3b
	s_mov_b32 s53, 0x3f317217
	ds_read_b128 v[116:119], v12 offset:0
	ds_read_b128 v[120:123], v12 offset:16
	ds_read_b128 v[124:127], v12 offset:32
	ds_read_b128 v[128:131], v12 offset:48
	v_mov_b32_e32 v32, v80
	s_waitcnt lgkmcnt(3)
	v_fmac_f32_e32 v32, v116, v64
	v_fmac_f32_e32 v32, v117, v65
	v_fmac_f32_e32 v32, v118, v66
	v_fmac_f32_e32 v32, v119, v67
	s_waitcnt lgkmcnt(2)
; DEVINL float logsig(float z) { return fminf(z, 0.f) - __logf(1.f + __expf(-fabsf(z))); }
; DEVINL void gla_prep_unit(const Params& p, int unit) {
;     ...
;     for (int i = 0; i < 64; ++i) {
;       float z = bias;
; #pragma unroll
;       for (int r = 0; r < 16; ++r) z += afab[i * 32 + dir * 16 + r] * u[r];
;       Gc[i * 128] = logsig(z) * (1.f / 16.f);
	v_fmac_f32_e32 v32, v120, v68
	v_fmac_f32_e32 v32, v121, v69
	v_fmac_f32_e32 v32, v122, v70
	v_fmac_f32_e32 v32, v123, v71
	s_waitcnt lgkmcnt(1)
	v_fmac_f32_e32 v32, v124, v72
	v_fmac_f32_e32 v32, v125, v73
	v_fmac_f32_e32 v32, v126, v74
	v_fmac_f32_e32 v32, v127, v75
	s_waitcnt lgkmcnt(0)
	v_fmac_f32_e32 v32, v128, v76
	v_fmac_f32_e32 v32, v129, v77
	v_fmac_f32_e32 v32, v130, v78
	v_fmac_f32_e32 v32, v131, v79
	v_min_f32_e32 v132, 0, v32
	v_mul_f32_e64 v32, |v32|, s52
	v_exp_f32_e32 v32, v32
	s_nop 0
	v_add_f32_e32 v32, 1.0, v32
	v_log_f32_e32 v32, v32
	s_nop 0
	v_mul_f32_e32 v133, 0x3f317217, v32
	v_fma_f32 v133, v32, s53, -v133
	v_fmac_f32_e32 v133, 0x3377d1cf, v32
	v_fmac_f32_e32 v133, 0x3f317217, v32
	v_sub_f32_e32 v32, v132, v133
	v_mul_f32_e32 v32, 0x3d800000, v32
	ds_read_b128 v[116:119], v12 offset:128
	ds_read_b128 v[120:123], v12 offset:144
	ds_read_b128 v[124:127], v12 offset:160
	ds_read_b128 v[128:131], v12 offset:176
	v_mov_b32_e32 v33, v80
	s_waitcnt lgkmcnt(3)
	v_fmac_f32_e32 v33, v116, v64
	v_fmac_f32_e32 v33, v117, v65
	v_fmac_f32_e32 v33, v118, v66
	v_fmac_f32_e32 v33, v119, v67
	s_waitcnt lgkmcnt(2)
	v_fmac_f32_e32 v33, v120, v68
	v_fmac_f32_e32 v33, v121, v69
	v_fmac_f32_e32 v33, v122, v70
	v_fmac_f32_e32 v33, v123, v71
	s_waitcnt lgkmcnt(1)
	v_fmac_f32_e32 v33, v124, v72
	v_fmac_f32_e32 v33, v125, v73
	v_fmac_f32_e32 v33, v126, v74
	v_fmac_f32_e32 v33, v127, v75
	s_waitcnt lgkmcnt(0)
	v_fmac_f32_e32 v33, v128, v76
	v_fmac_f32_e32 v33, v129, v77
	v_fmac_f32_e32 v33, v130, v78
	v_fmac_f32_e32 v33, v131, v79
	v_min_f32_e32 v132, 0, v33
	v_mul_f32_e64 v33, |v33|, s52
	v_exp_f32_e32 v33, v33
	s_nop 0
	v_add_f32_e32 v33, 1.0, v33
	v_log_f32_e32 v33, v33
	s_nop 0
	v_mul_f32_e32 v133, 0x3f317217, v33
	v_fma_f32 v133, v33, s53, -v133
	v_fmac_f32_e32 v133, 0x3377d1cf, v33
	v_fmac_f32_e32 v133, 0x3f317217, v33
	v_sub_f32_e32 v33, v132, v133
	v_mul_f32_e32 v33, 0x3d800000, v33
	ds_read_b128 v[116:119], v12 offset:256
	ds_read_b128 v[120:123], v12 offset:272
	ds_read_b128 v[124:127], v12 offset:288
	ds_read_b128 v[128:131], v12 offset:304
	v_mov_b32_e32 v34, v80
	s_waitcnt lgkmcnt(3)
	v_fmac_f32_e32 v34, v116, v64
	v_fmac_f32_e32 v34, v117, v65
	v_fmac_f32_e32 v34, v118, v66
	v_fmac_f32_e32 v34, v119, v67
	s_waitcnt lgkmcnt(2)
	v_fmac_f32_e32 v34, v120, v68
	v_fmac_f32_e32 v34, v121, v69
	v_fmac_f32_e32 v34, v122, v70
	v_fmac_f32_e32 v34, v123, v71
	s_waitcnt lgkmcnt(1)
	v_fmac_f32_e32 v34, v124, v72
	v_fmac_f32_e32 v34, v125, v73
	v_fmac_f32_e32 v34, v126, v74
	v_fmac_f32_e32 v34, v127, v75
	s_waitcnt lgkmcnt(0)
	v_fmac_f32_e32 v34, v128, v76
	v_fmac_f32_e32 v34, v129, v77
	v_fmac_f32_e32 v34, v130, v78
	v_fmac_f32_e32 v34, v131, v79
	v_min_f32_e32 v132, 0, v34
	v_mul_f32_e64 v34, |v34|, s52
	v_exp_f32_e32 v34, v34
	s_nop 0
	v_add_f32_e32 v34, 1.0, v34
	v_log_f32_e32 v34, v34
	s_nop 0
	v_mul_f32_e32 v133, 0x3f317217, v34
	v_fma_f32 v133, v34, s53, -v133
	v_fmac_f32_e32 v133, 0x3377d1cf, v34
	v_fmac_f32_e32 v133, 0x3f317217, v34
	v_sub_f32_e32 v34, v132, v133
	v_mul_f32_e32 v34, 0x3d800000, v34
	ds_read_b128 v[116:119], v12 offset:384
	ds_read_b128 v[120:123], v12 offset:400
	ds_read_b128 v[124:127], v12 offset:416
	ds_read_b128 v[128:131], v12 offset:432
	v_mov_b32_e32 v35, v80
	s_waitcnt lgkmcnt(3)
	v_fmac_f32_e32 v35, v116, v64
	v_fmac_f32_e32 v35, v117, v65
	v_fmac_f32_e32 v35, v118, v66
	v_fmac_f32_e32 v35, v119, v67
	s_waitcnt lgkmcnt(2)
	v_fmac_f32_e32 v35, v120, v68
	v_fmac_f32_e32 v35, v121, v69
	v_fmac_f32_e32 v35, v122, v70
	v_fmac_f32_e32 v35, v123, v71
	s_waitcnt lgkmcnt(1)
	v_fmac_f32_e32 v35, v124, v72
	v_fmac_f32_e32 v35, v125, v73
	v_fmac_f32_e32 v35, v126, v74
	v_fmac_f32_e32 v35, v127, v75
	s_waitcnt lgkmcnt(0)
	v_fmac_f32_e32 v35, v128, v76
	v_fmac_f32_e32 v35, v129, v77
	v_fmac_f32_e32 v35, v130, v78
	v_fmac_f32_e32 v35, v131, v79
	v_min_f32_e32 v132, 0, v35
	v_mul_f32_e64 v35, |v35|, s52
	v_exp_f32_e32 v35, v35
	s_nop 0
	v_add_f32_e32 v35, 1.0, v35
	v_log_f32_e32 v35, v35
	s_nop 0
	v_mul_f32_e32 v133, 0x3f317217, v35
	v_fma_f32 v133, v35, s53, -v133
	v_fmac_f32_e32 v133, 0x3377d1cf, v35
	v_fmac_f32_e32 v133, 0x3f317217, v35
	v_sub_f32_e32 v35, v132, v133
	v_mul_f32_e32 v35, 0x3d800000, v35
	ds_read_b128 v[116:119], v12 offset:512
	ds_read_b128 v[120:123], v12 offset:528
	ds_read_b128 v[124:127], v12 offset:544
	ds_read_b128 v[128:131], v12 offset:560
	v_mov_b32_e32 v36, v80
	s_waitcnt lgkmcnt(3)
	v_fmac_f32_e32 v36, v116, v64
	v_fmac_f32_e32 v36, v117, v65
	v_fmac_f32_e32 v36, v118, v66
	v_fmac_f32_e32 v36, v119, v67
	s_waitcnt lgkmcnt(2)
	v_fmac_f32_e32 v36, v120, v68
	v_fmac_f32_e32 v36, v121, v69
	v_fmac_f32_e32 v36, v122, v70
	v_fmac_f32_e32 v36, v123, v71
	s_waitcnt lgkmcnt(1)
	v_fmac_f32_e32 v36, v124, v72
	v_fmac_f32_e32 v36, v125, v73
	v_fmac_f32_e32 v36, v126, v74
	v_fmac_f32_e32 v36, v127, v75
	s_waitcnt lgkmcnt(0)
	v_fmac_f32_e32 v36, v128, v76
	v_fmac_f32_e32 v36, v129, v77
	v_fmac_f32_e32 v36, v130, v78
	v_fmac_f32_e32 v36, v131, v79
	v_min_f32_e32 v132, 0, v36
	v_mul_f32_e64 v36, |v36|, s52
	v_exp_f32_e32 v36, v36
	s_nop 0
	v_add_f32_e32 v36, 1.0, v36
	v_log_f32_e32 v36, v36
	s_nop 0
	v_mul_f32_e32 v133, 0x3f317217, v36
	v_fma_f32 v133, v36, s53, -v133
	v_fmac_f32_e32 v133, 0x3377d1cf, v36
	v_fmac_f32_e32 v133, 0x3f317217, v36
	v_sub_f32_e32 v36, v132, v133
	v_mul_f32_e32 v36, 0x3d800000, v36
	ds_read_b128 v[116:119], v12 offset:640
	ds_read_b128 v[120:123], v12 offset:656
	ds_read_b128 v[124:127], v12 offset:672
	ds_read_b128 v[128:131], v12 offset:688
	v_mov_b32_e32 v37, v80
	s_waitcnt lgkmcnt(3)
	v_fmac_f32_e32 v37, v116, v64
	v_fmac_f32_e32 v37, v117, v65
	v_fmac_f32_e32 v37, v118, v66
	v_fmac_f32_e32 v37, v119, v67
	s_waitcnt lgkmcnt(2)
; DEVINL float logsig(float z) { return fminf(z, 0.f) - __logf(1.f + __expf(-fabsf(z))); }
; DEVINL void gla_prep_unit(const Params& p, int unit) {
;     ...
;     for (int i = 0; i < 64; ++i) {
;       float z = bias;
; #pragma unroll
;       for (int r = 0; r < 16; ++r) z += afab[i * 32 + dir * 16 + r] * u[r];
;       Gc[i * 128] = logsig(z) * (1.f / 16.f);
	v_fmac_f32_e32 v37, v120, v68
	v_fmac_f32_e32 v37, v121, v69
	v_fmac_f32_e32 v37, v122, v70
	v_fmac_f32_e32 v37, v123, v71
	s_waitcnt lgkmcnt(1)
	v_fmac_f32_e32 v37, v124, v72
	v_fmac_f32_e32 v37, v125, v73
	v_fmac_f32_e32 v37, v126, v74
	v_fmac_f32_e32 v37, v127, v75
	s_waitcnt lgkmcnt(0)
	v_fmac_f32_e32 v37, v128, v76
	v_fmac_f32_e32 v37, v129, v77
	v_fmac_f32_e32 v37, v130, v78
	v_fmac_f32_e32 v37, v131, v79
	v_min_f32_e32 v132, 0, v37
	v_mul_f32_e64 v37, |v37|, s52
	v_exp_f32_e32 v37, v37
	s_nop 0
	v_add_f32_e32 v37, 1.0, v37
	v_log_f32_e32 v37, v37
	s_nop 0
	v_mul_f32_e32 v133, 0x3f317217, v37
	v_fma_f32 v133, v37, s53, -v133
	v_fmac_f32_e32 v133, 0x3377d1cf, v37
	v_fmac_f32_e32 v133, 0x3f317217, v37
	v_sub_f32_e32 v37, v132, v133
	v_mul_f32_e32 v37, 0x3d800000, v37
	ds_read_b128 v[116:119], v12 offset:768
	ds_read_b128 v[120:123], v12 offset:784
	ds_read_b128 v[124:127], v12 offset:800
	ds_read_b128 v[128:131], v12 offset:816
	v_mov_b32_e32 v38, v80
	s_waitcnt lgkmcnt(3)
	v_fmac_f32_e32 v38, v116, v64
	v_fmac_f32_e32 v38, v117, v65
	v_fmac_f32_e32 v38, v118, v66
	v_fmac_f32_e32 v38, v119, v67
	s_waitcnt lgkmcnt(2)
	v_fmac_f32_e32 v38, v120, v68
	v_fmac_f32_e32 v38, v121, v69
	v_fmac_f32_e32 v38, v122, v70
	v_fmac_f32_e32 v38, v123, v71
	s_waitcnt lgkmcnt(1)
	v_fmac_f32_e32 v38, v124, v72
	v_fmac_f32_e32 v38, v125, v73
	v_fmac_f32_e32 v38, v126, v74
	v_fmac_f32_e32 v38, v127, v75
	s_waitcnt lgkmcnt(0)
	v_fmac_f32_e32 v38, v128, v76
	v_fmac_f32_e32 v38, v129, v77
	v_fmac_f32_e32 v38, v130, v78
	v_fmac_f32_e32 v38, v131, v79
	v_min_f32_e32 v132, 0, v38
	v_mul_f32_e64 v38, |v38|, s52
	v_exp_f32_e32 v38, v38
	s_nop 0
	v_add_f32_e32 v38, 1.0, v38
	v_log_f32_e32 v38, v38
	s_nop 0
	v_mul_f32_e32 v133, 0x3f317217, v38
	v_fma_f32 v133, v38, s53, -v133
	v_fmac_f32_e32 v133, 0x3377d1cf, v38
	v_fmac_f32_e32 v133, 0x3f317217, v38
	v_sub_f32_e32 v38, v132, v133
	v_mul_f32_e32 v38, 0x3d800000, v38
	ds_read_b128 v[116:119], v12 offset:896
	ds_read_b128 v[120:123], v12 offset:912
	ds_read_b128 v[124:127], v12 offset:928
	ds_read_b128 v[128:131], v12 offset:944
	v_mov_b32_e32 v39, v80
	s_waitcnt lgkmcnt(3)
	v_fmac_f32_e32 v39, v116, v64
	v_fmac_f32_e32 v39, v117, v65
	v_fmac_f32_e32 v39, v118, v66
	v_fmac_f32_e32 v39, v119, v67
	s_waitcnt lgkmcnt(2)
	v_fmac_f32_e32 v39, v120, v68
	v_fmac_f32_e32 v39, v121, v69
	v_fmac_f32_e32 v39, v122, v70
	v_fmac_f32_e32 v39, v123, v71
	s_waitcnt lgkmcnt(1)
	v_fmac_f32_e32 v39, v124, v72
	v_fmac_f32_e32 v39, v125, v73
	v_fmac_f32_e32 v39, v126, v74
	v_fmac_f32_e32 v39, v127, v75
	s_waitcnt lgkmcnt(0)
	v_fmac_f32_e32 v39, v128, v76
	v_fmac_f32_e32 v39, v129, v77
	v_fmac_f32_e32 v39, v130, v78
	v_fmac_f32_e32 v39, v131, v79
	v_min_f32_e32 v132, 0, v39
	v_mul_f32_e64 v39, |v39|, s52
	v_exp_f32_e32 v39, v39
	s_nop 0
	v_add_f32_e32 v39, 1.0, v39
	v_log_f32_e32 v39, v39
	s_nop 0
	v_mul_f32_e32 v133, 0x3f317217, v39
	v_fma_f32 v133, v39, s53, -v133
	v_fmac_f32_e32 v133, 0x3377d1cf, v39
	v_fmac_f32_e32 v133, 0x3f317217, v39
	v_sub_f32_e32 v39, v132, v133
	v_mul_f32_e32 v39, 0x3d800000, v39
	ds_read_b128 v[116:119], v12 offset:1024
	ds_read_b128 v[120:123], v12 offset:1040
	ds_read_b128 v[124:127], v12 offset:1056
	ds_read_b128 v[128:131], v12 offset:1072
	v_mov_b32_e32 v40, v80
	s_waitcnt lgkmcnt(3)
	v_fmac_f32_e32 v40, v116, v64
	v_fmac_f32_e32 v40, v117, v65
	v_fmac_f32_e32 v40, v118, v66
	v_fmac_f32_e32 v40, v119, v67
	s_waitcnt lgkmcnt(2)
	v_fmac_f32_e32 v40, v120, v68
	v_fmac_f32_e32 v40, v121, v69
	v_fmac_f32_e32 v40, v122, v70
	v_fmac_f32_e32 v40, v123, v71
	s_waitcnt lgkmcnt(1)
	v_fmac_f32_e32 v40, v124, v72
	v_fmac_f32_e32 v40, v125, v73
	v_fmac_f32_e32 v40, v126, v74
	v_fmac_f32_e32 v40, v127, v75
	s_waitcnt lgkmcnt(0)
	v_fmac_f32_e32 v40, v128, v76
	v_fmac_f32_e32 v40, v129, v77
	v_fmac_f32_e32 v40, v130, v78
	v_fmac_f32_e32 v40, v131, v79
	v_min_f32_e32 v132, 0, v40
	v_mul_f32_e64 v40, |v40|, s52
	v_exp_f32_e32 v40, v40
	s_nop 0
	v_add_f32_e32 v40, 1.0, v40
	v_log_f32_e32 v40, v40
	s_nop 0
	v_mul_f32_e32 v133, 0x3f317217, v40
	v_fma_f32 v133, v40, s53, -v133
	v_fmac_f32_e32 v133, 0x3377d1cf, v40
	v_fmac_f32_e32 v133, 0x3f317217, v40
	v_sub_f32_e32 v40, v132, v133
	v_mul_f32_e32 v40, 0x3d800000, v40
	ds_read_b128 v[116:119], v12 offset:1152
	ds_read_b128 v[120:123], v12 offset:1168
	ds_read_b128 v[124:127], v12 offset:1184
	ds_read_b128 v[128:131], v12 offset:1200
	v_mov_b32_e32 v41, v80
	s_waitcnt lgkmcnt(3)
	v_fmac_f32_e32 v41, v116, v64
	v_fmac_f32_e32 v41, v117, v65
	v_fmac_f32_e32 v41, v118, v66
	v_fmac_f32_e32 v41, v119, v67
	s_waitcnt lgkmcnt(2)
	v_fmac_f32_e32 v41, v120, v68
	v_fmac_f32_e32 v41, v121, v69
	v_fmac_f32_e32 v41, v122, v70
	v_fmac_f32_e32 v41, v123, v71
	s_waitcnt lgkmcnt(1)
	v_fmac_f32_e32 v41, v124, v72
	v_fmac_f32_e32 v41, v125, v73
	v_fmac_f32_e32 v41, v126, v74
	v_fmac_f32_e32 v41, v127, v75
	s_waitcnt lgkmcnt(0)
	v_fmac_f32_e32 v41, v128, v76
	v_fmac_f32_e32 v41, v129, v77
	v_fmac_f32_e32 v41, v130, v78
	v_fmac_f32_e32 v41, v131, v79
	v_min_f32_e32 v132, 0, v41
	v_mul_f32_e64 v41, |v41|, s52
	v_exp_f32_e32 v41, v41
	s_nop 0
	v_add_f32_e32 v41, 1.0, v41
	v_log_f32_e32 v41, v41
	s_nop 0
	v_mul_f32_e32 v133, 0x3f317217, v41
	v_fma_f32 v133, v41, s53, -v133
	v_fmac_f32_e32 v133, 0x3377d1cf, v41
	v_fmac_f32_e32 v133, 0x3f317217, v41
	v_sub_f32_e32 v41, v132, v133
	v_mul_f32_e32 v41, 0x3d800000, v41
	ds_read_b128 v[116:119], v12 offset:1280
	ds_read_b128 v[120:123], v12 offset:1296
	ds_read_b128 v[124:127], v12 offset:1312
	ds_read_b128 v[128:131], v12 offset:1328
	v_mov_b32_e32 v42, v80
	s_waitcnt lgkmcnt(3)
	v_fmac_f32_e32 v42, v116, v64
	v_fmac_f32_e32 v42, v117, v65
	v_fmac_f32_e32 v42, v118, v66
	v_fmac_f32_e32 v42, v119, v67
	s_waitcnt lgkmcnt(2)
; DEVINL float logsig(float z) { return fminf(z, 0.f) - __logf(1.f + __expf(-fabsf(z))); }
; DEVINL void gla_prep_unit(const Params& p, int unit) {
;     ...
;     for (int i = 0; i < 64; ++i) {
;       float z = bias;
; #pragma unroll
;       for (int r = 0; r < 16; ++r) z += afab[i * 32 + dir * 16 + r] * u[r];
;       Gc[i * 128] = logsig(z) * (1.f / 16.f);
	v_fmac_f32_e32 v42, v120, v68
	v_fmac_f32_e32 v42, v121, v69
	v_fmac_f32_e32 v42, v122, v70
	v_fmac_f32_e32 v42, v123, v71
	s_waitcnt lgkmcnt(1)
	v_fmac_f32_e32 v42, v124, v72
	v_fmac_f32_e32 v42, v125, v73
	v_fmac_f32_e32 v42, v126, v74
	v_fmac_f32_e32 v42, v127, v75
	s_waitcnt lgkmcnt(0)
	v_fmac_f32_e32 v42, v128, v76
	v_fmac_f32_e32 v42, v129, v77
	v_fmac_f32_e32 v42, v130, v78
	v_fmac_f32_e32 v42, v131, v79
	v_min_f32_e32 v132, 0, v42
	v_mul_f32_e64 v42, |v42|, s52
	v_exp_f32_e32 v42, v42
	s_nop 0
	v_add_f32_e32 v42, 1.0, v42
	v_log_f32_e32 v42, v42
	s_nop 0
	v_mul_f32_e32 v133, 0x3f317217, v42
	v_fma_f32 v133, v42, s53, -v133
	v_fmac_f32_e32 v133, 0x3377d1cf, v42
	v_fmac_f32_e32 v133, 0x3f317217, v42
	v_sub_f32_e32 v42, v132, v133
	v_mul_f32_e32 v42, 0x3d800000, v42
	ds_read_b128 v[116:119], v12 offset:1408
	ds_read_b128 v[120:123], v12 offset:1424
	ds_read_b128 v[124:127], v12 offset:1440
	ds_read_b128 v[128:131], v12 offset:1456
	v_mov_b32_e32 v43, v80
	s_waitcnt lgkmcnt(3)
	v_fmac_f32_e32 v43, v116, v64
	v_fmac_f32_e32 v43, v117, v65
	v_fmac_f32_e32 v43, v118, v66
	v_fmac_f32_e32 v43, v119, v67
	s_waitcnt lgkmcnt(2)
	v_fmac_f32_e32 v43, v120, v68
	v_fmac_f32_e32 v43, v121, v69
	v_fmac_f32_e32 v43, v122, v70
	v_fmac_f32_e32 v43, v123, v71
	s_waitcnt lgkmcnt(1)
	v_fmac_f32_e32 v43, v124, v72
	v_fmac_f32_e32 v43, v125, v73
	v_fmac_f32_e32 v43, v126, v74
	v_fmac_f32_e32 v43, v127, v75
	s_waitcnt lgkmcnt(0)
	v_fmac_f32_e32 v43, v128, v76
	v_fmac_f32_e32 v43, v129, v77
	v_fmac_f32_e32 v43, v130, v78
	v_fmac_f32_e32 v43, v131, v79
	v_min_f32_e32 v132, 0, v43
	v_mul_f32_e64 v43, |v43|, s52
	v_exp_f32_e32 v43, v43
	s_nop 0
	v_add_f32_e32 v43, 1.0, v43
	v_log_f32_e32 v43, v43
	s_nop 0
	v_mul_f32_e32 v133, 0x3f317217, v43
	v_fma_f32 v133, v43, s53, -v133
	v_fmac_f32_e32 v133, 0x3377d1cf, v43
	v_fmac_f32_e32 v133, 0x3f317217, v43
	v_sub_f32_e32 v43, v132, v133
	v_mul_f32_e32 v43, 0x3d800000, v43
	ds_read_b128 v[116:119], v12 offset:1536
	ds_read_b128 v[120:123], v12 offset:1552
	ds_read_b128 v[124:127], v12 offset:1568
	ds_read_b128 v[128:131], v12 offset:1584
	v_mov_b32_e32 v44, v80
	s_waitcnt lgkmcnt(3)
	v_fmac_f32_e32 v44, v116, v64
	v_fmac_f32_e32 v44, v117, v65
	v_fmac_f32_e32 v44, v118, v66
	v_fmac_f32_e32 v44, v119, v67
	s_waitcnt lgkmcnt(2)
	v_fmac_f32_e32 v44, v120, v68
	v_fmac_f32_e32 v44, v121, v69
	v_fmac_f32_e32 v44, v122, v70
	v_fmac_f32_e32 v44, v123, v71
	s_waitcnt lgkmcnt(1)
	v_fmac_f32_e32 v44, v124, v72
	v_fmac_f32_e32 v44, v125, v73
	v_fmac_f32_e32 v44, v126, v74
	v_fmac_f32_e32 v44, v127, v75
	s_waitcnt lgkmcnt(0)
	v_fmac_f32_e32 v44, v128, v76
	v_fmac_f32_e32 v44, v129, v77
	v_fmac_f32_e32 v44, v130, v78
	v_fmac_f32_e32 v44, v131, v79
	v_min_f32_e32 v132, 0, v44
	v_mul_f32_e64 v44, |v44|, s52
	v_exp_f32_e32 v44, v44
	s_nop 0
	v_add_f32_e32 v44, 1.0, v44
	v_log_f32_e32 v44, v44
	s_nop 0
	v_mul_f32_e32 v133, 0x3f317217, v44
	v_fma_f32 v133, v44, s53, -v133
	v_fmac_f32_e32 v133, 0x3377d1cf, v44
	v_fmac_f32_e32 v133, 0x3f317217, v44
	v_sub_f32_e32 v44, v132, v133
	v_mul_f32_e32 v44, 0x3d800000, v44
	ds_read_b128 v[116:119], v12 offset:1664
	ds_read_b128 v[120:123], v12 offset:1680
	ds_read_b128 v[124:127], v12 offset:1696
	ds_read_b128 v[128:131], v12 offset:1712
	v_mov_b32_e32 v45, v80
	s_waitcnt lgkmcnt(3)
	v_fmac_f32_e32 v45, v116, v64
	v_fmac_f32_e32 v45, v117, v65
	v_fmac_f32_e32 v45, v118, v66
	v_fmac_f32_e32 v45, v119, v67
	s_waitcnt lgkmcnt(2)
	v_fmac_f32_e32 v45, v120, v68
	v_fmac_f32_e32 v45, v121, v69
	v_fmac_f32_e32 v45, v122, v70
	v_fmac_f32_e32 v45, v123, v71
	s_waitcnt lgkmcnt(1)
	v_fmac_f32_e32 v45, v124, v72
	v_fmac_f32_e32 v45, v125, v73
	v_fmac_f32_e32 v45, v126, v74
	v_fmac_f32_e32 v45, v127, v75
	s_waitcnt lgkmcnt(0)
	v_fmac_f32_e32 v45, v128, v76
	v_fmac_f32_e32 v45, v129, v77
	v_fmac_f32_e32 v45, v130, v78
	v_fmac_f32_e32 v45, v131, v79
	v_min_f32_e32 v132, 0, v45
	v_mul_f32_e64 v45, |v45|, s52
	v_exp_f32_e32 v45, v45
	s_nop 0
	v_add_f32_e32 v45, 1.0, v45
	v_log_f32_e32 v45, v45
	s_nop 0
	v_mul_f32_e32 v133, 0x3f317217, v45
	v_fma_f32 v133, v45, s53, -v133
	v_fmac_f32_e32 v133, 0x3377d1cf, v45
	v_fmac_f32_e32 v133, 0x3f317217, v45
	v_sub_f32_e32 v45, v132, v133
	v_mul_f32_e32 v45, 0x3d800000, v45
	ds_read_b128 v[116:119], v12 offset:1792
	ds_read_b128 v[120:123], v12 offset:1808
	ds_read_b128 v[124:127], v12 offset:1824
	ds_read_b128 v[128:131], v12 offset:1840
	v_mov_b32_e32 v46, v80
	s_waitcnt lgkmcnt(3)
	v_fmac_f32_e32 v46, v116, v64
	v_fmac_f32_e32 v46, v117, v65
	v_fmac_f32_e32 v46, v118, v66
	v_fmac_f32_e32 v46, v119, v67
	s_waitcnt lgkmcnt(2)
	v_fmac_f32_e32 v46, v120, v68
	v_fmac_f32_e32 v46, v121, v69
	v_fmac_f32_e32 v46, v122, v70
	v_fmac_f32_e32 v46, v123, v71
	s_waitcnt lgkmcnt(1)
	v_fmac_f32_e32 v46, v124, v72
	v_fmac_f32_e32 v46, v125, v73
	v_fmac_f32_e32 v46, v126, v74
	v_fmac_f32_e32 v46, v127, v75
	s_waitcnt lgkmcnt(0)
	v_fmac_f32_e32 v46, v128, v76
	v_fmac_f32_e32 v46, v129, v77
	v_fmac_f32_e32 v46, v130, v78
	v_fmac_f32_e32 v46, v131, v79
	v_min_f32_e32 v132, 0, v46
	v_mul_f32_e64 v46, |v46|, s52
	v_exp_f32_e32 v46, v46
	s_nop 0
	v_add_f32_e32 v46, 1.0, v46
	v_log_f32_e32 v46, v46
	s_nop 0
	v_mul_f32_e32 v133, 0x3f317217, v46
	v_fma_f32 v133, v46, s53, -v133
	v_fmac_f32_e32 v133, 0x3377d1cf, v46
	v_fmac_f32_e32 v133, 0x3f317217, v46
	v_sub_f32_e32 v46, v132, v133
	v_mul_f32_e32 v46, 0x3d800000, v46
	ds_read_b128 v[116:119], v12 offset:1920
	ds_read_b128 v[120:123], v12 offset:1936
	ds_read_b128 v[124:127], v12 offset:1952
	ds_read_b128 v[128:131], v12 offset:1968
	v_mov_b32_e32 v47, v80
	s_waitcnt lgkmcnt(3)
; DEVINL float logsig(float z) { return fminf(z, 0.f) - __logf(1.f + __expf(-fabsf(z))); }
; DEVINL void gla_prep_unit(const Params& p, int unit) {
;     ...
;     for (int i = 0; i < 64; ++i) {
;       float z = bias;
; #pragma unroll
;       for (int r = 0; r < 16; ++r) z += afab[i * 32 + dir * 16 + r] * u[r];
;       Gc[i * 128] = logsig(z) * (1.f / 16.f);
	v_fmac_f32_e32 v47, v116, v64
	v_fmac_f32_e32 v47, v117, v65
	v_fmac_f32_e32 v47, v118, v66
	v_fmac_f32_e32 v47, v119, v67
	s_waitcnt lgkmcnt(2)
	v_fmac_f32_e32 v47, v120, v68
	v_fmac_f32_e32 v47, v121, v69
	v_fmac_f32_e32 v47, v122, v70
	v_fmac_f32_e32 v47, v123, v71
	s_waitcnt lgkmcnt(1)
	v_fmac_f32_e32 v47, v124, v72
	v_fmac_f32_e32 v47, v125, v73
	v_fmac_f32_e32 v47, v126, v74
	v_fmac_f32_e32 v47, v127, v75
	s_waitcnt lgkmcnt(0)
	v_fmac_f32_e32 v47, v128, v76
	v_fmac_f32_e32 v47, v129, v77
	v_fmac_f32_e32 v47, v130, v78
	v_fmac_f32_e32 v47, v131, v79
	v_min_f32_e32 v132, 0, v47
	v_mul_f32_e64 v47, |v47|, s52
	v_exp_f32_e32 v47, v47
	s_nop 0
	v_add_f32_e32 v47, 1.0, v47
	v_log_f32_e32 v47, v47
	s_nop 0
	v_mul_f32_e32 v133, 0x3f317217, v47
	v_fma_f32 v133, v47, s53, -v133
	v_fmac_f32_e32 v133, 0x3377d1cf, v47
	v_fmac_f32_e32 v133, 0x3f317217, v47
	v_sub_f32_e32 v47, v132, v133
	v_mul_f32_e32 v47, 0x3d800000, v47
	ds_read_b128 v[116:119], v12 offset:2048
	ds_read_b128 v[120:123], v12 offset:2064
	ds_read_b128 v[124:127], v12 offset:2080
	ds_read_b128 v[128:131], v12 offset:2096
	v_mov_b32_e32 v48, v80
	s_waitcnt lgkmcnt(3)
	v_fmac_f32_e32 v48, v116, v64
	v_fmac_f32_e32 v48, v117, v65
	v_fmac_f32_e32 v48, v118, v66
	v_fmac_f32_e32 v48, v119, v67
	s_waitcnt lgkmcnt(2)
	v_fmac_f32_e32 v48, v120, v68
	v_fmac_f32_e32 v48, v121, v69
	v_fmac_f32_e32 v48, v122, v70
	v_fmac_f32_e32 v48, v123, v71
	s_waitcnt lgkmcnt(1)
	v_fmac_f32_e32 v48, v124, v72
	v_fmac_f32_e32 v48, v125, v73
	v_fmac_f32_e32 v48, v126, v74
	v_fmac_f32_e32 v48, v127, v75
	s_waitcnt lgkmcnt(0)
	v_fmac_f32_e32 v48, v128, v76
	v_fmac_f32_e32 v48, v129, v77
	v_fmac_f32_e32 v48, v130, v78
	v_fmac_f32_e32 v48, v131, v79
	v_min_f32_e32 v132, 0, v48
	v_mul_f32_e64 v48, |v48|, s52
	v_exp_f32_e32 v48, v48
	s_nop 0
	v_add_f32_e32 v48, 1.0, v48
	v_log_f32_e32 v48, v48
	s_nop 0
	v_mul_f32_e32 v133, 0x3f317217, v48
	v_fma_f32 v133, v48, s53, -v133
	v_fmac_f32_e32 v133, 0x3377d1cf, v48
	v_fmac_f32_e32 v133, 0x3f317217, v48
	v_sub_f32_e32 v48, v132, v133
	v_mul_f32_e32 v48, 0x3d800000, v48
	ds_read_b128 v[116:119], v12 offset:2176
	ds_read_b128 v[120:123], v12 offset:2192
	ds_read_b128 v[124:127], v12 offset:2208
	ds_read_b128 v[128:131], v12 offset:2224
	v_mov_b32_e32 v49, v80
	s_waitcnt lgkmcnt(3)
	v_fmac_f32_e32 v49, v116, v64
	v_fmac_f32_e32 v49, v117, v65
	v_fmac_f32_e32 v49, v118, v66
	v_fmac_f32_e32 v49, v119, v67
	s_waitcnt lgkmcnt(2)
	v_fmac_f32_e32 v49, v120, v68
	v_fmac_f32_e32 v49, v121, v69
	v_fmac_f32_e32 v49, v122, v70
	v_fmac_f32_e32 v49, v123, v71
	s_waitcnt lgkmcnt(1)
	v_fmac_f32_e32 v49, v124, v72
	v_fmac_f32_e32 v49, v125, v73
	v_fmac_f32_e32 v49, v126, v74
	v_fmac_f32_e32 v49, v127, v75
	s_waitcnt lgkmcnt(0)
	v_fmac_f32_e32 v49, v128, v76
	v_fmac_f32_e32 v49, v129, v77
	v_fmac_f32_e32 v49, v130, v78
	v_fmac_f32_e32 v49, v131, v79
	v_min_f32_e32 v132, 0, v49
	v_mul_f32_e64 v49, |v49|, s52
	v_exp_f32_e32 v49, v49
	s_nop 0
	v_add_f32_e32 v49, 1.0, v49
	v_log_f32_e32 v49, v49
	s_nop 0
	v_mul_f32_e32 v133, 0x3f317217, v49
	v_fma_f32 v133, v49, s53, -v133
	v_fmac_f32_e32 v133, 0x3377d1cf, v49
	v_fmac_f32_e32 v133, 0x3f317217, v49
	v_sub_f32_e32 v49, v132, v133
	v_mul_f32_e32 v49, 0x3d800000, v49
	ds_read_b128 v[116:119], v12 offset:2304
	ds_read_b128 v[120:123], v12 offset:2320
	ds_read_b128 v[124:127], v12 offset:2336
	ds_read_b128 v[128:131], v12 offset:2352
	v_mov_b32_e32 v50, v80
	s_waitcnt lgkmcnt(3)
	v_fmac_f32_e32 v50, v116, v64
	v_fmac_f32_e32 v50, v117, v65
	v_fmac_f32_e32 v50, v118, v66
	v_fmac_f32_e32 v50, v119, v67
	s_waitcnt lgkmcnt(2)
	v_fmac_f32_e32 v50, v120, v68
	v_fmac_f32_e32 v50, v121, v69
	v_fmac_f32_e32 v50, v122, v70
	v_fmac_f32_e32 v50, v123, v71
	s_waitcnt lgkmcnt(1)
	v_fmac_f32_e32 v50, v124, v72
	v_fmac_f32_e32 v50, v125, v73
	v_fmac_f32_e32 v50, v126, v74
	v_fmac_f32_e32 v50, v127, v75
	s_waitcnt lgkmcnt(0)
	v_fmac_f32_e32 v50, v128, v76
	v_fmac_f32_e32 v50, v129, v77
	v_fmac_f32_e32 v50, v130, v78
	v_fmac_f32_e32 v50, v131, v79
	v_min_f32_e32 v132, 0, v50
	v_mul_f32_e64 v50, |v50|, s52
	v_exp_f32_e32 v50, v50
	s_nop 0
	v_add_f32_e32 v50, 1.0, v50
	v_log_f32_e32 v50, v50
	s_nop 0
	v_mul_f32_e32 v133, 0x3f317217, v50
	v_fma_f32 v133, v50, s53, -v133
	v_fmac_f32_e32 v133, 0x3377d1cf, v50
	v_fmac_f32_e32 v133, 0x3f317217, v50
	v_sub_f32_e32 v50, v132, v133
	v_mul_f32_e32 v50, 0x3d800000, v50
	ds_read_b128 v[116:119], v12 offset:2432
	ds_read_b128 v[120:123], v12 offset:2448
	ds_read_b128 v[124:127], v12 offset:2464
	ds_read_b128 v[128:131], v12 offset:2480
	v_mov_b32_e32 v51, v80
	s_waitcnt lgkmcnt(3)
	v_fmac_f32_e32 v51, v116, v64
	v_fmac_f32_e32 v51, v117, v65
	v_fmac_f32_e32 v51, v118, v66
	v_fmac_f32_e32 v51, v119, v67
	s_waitcnt lgkmcnt(2)
	v_fmac_f32_e32 v51, v120, v68
	v_fmac_f32_e32 v51, v121, v69
	v_fmac_f32_e32 v51, v122, v70
	v_fmac_f32_e32 v51, v123, v71
	s_waitcnt lgkmcnt(1)
	v_fmac_f32_e32 v51, v124, v72
	v_fmac_f32_e32 v51, v125, v73
	v_fmac_f32_e32 v51, v126, v74
	v_fmac_f32_e32 v51, v127, v75
	s_waitcnt lgkmcnt(0)
	v_fmac_f32_e32 v51, v128, v76
	v_fmac_f32_e32 v51, v129, v77
	v_fmac_f32_e32 v51, v130, v78
	v_fmac_f32_e32 v51, v131, v79
	v_min_f32_e32 v132, 0, v51
	v_mul_f32_e64 v51, |v51|, s52
	v_exp_f32_e32 v51, v51
	s_nop 0
	v_add_f32_e32 v51, 1.0, v51
	v_log_f32_e32 v51, v51
	s_nop 0
	v_mul_f32_e32 v133, 0x3f317217, v51
	v_fma_f32 v133, v51, s53, -v133
	v_fmac_f32_e32 v133, 0x3377d1cf, v51
	v_fmac_f32_e32 v133, 0x3f317217, v51
	v_sub_f32_e32 v51, v132, v133
	v_mul_f32_e32 v51, 0x3d800000, v51
	ds_read_b128 v[116:119], v12 offset:2560
	ds_read_b128 v[120:123], v12 offset:2576
	ds_read_b128 v[124:127], v12 offset:2592
	ds_read_b128 v[128:131], v12 offset:2608
	v_mov_b32_e32 v52, v80
	s_waitcnt lgkmcnt(3)
; DEVINL float logsig(float z) { return fminf(z, 0.f) - __logf(1.f + __expf(-fabsf(z))); }
; DEVINL void gla_prep_unit(const Params& p, int unit) {
;     ...
;     for (int i = 0; i < 64; ++i) {
;       float z = bias;
; #pragma unroll
;       for (int r = 0; r < 16; ++r) z += afab[i * 32 + dir * 16 + r] * u[r];
;       Gc[i * 128] = logsig(z) * (1.f / 16.f);
	v_fmac_f32_e32 v52, v116, v64
	v_fmac_f32_e32 v52, v117, v65
	v_fmac_f32_e32 v52, v118, v66
	v_fmac_f32_e32 v52, v119, v67
	s_waitcnt lgkmcnt(2)
	v_fmac_f32_e32 v52, v120, v68
	v_fmac_f32_e32 v52, v121, v69
	v_fmac_f32_e32 v52, v122, v70
	v_fmac_f32_e32 v52, v123, v71
	s_waitcnt lgkmcnt(1)
	v_fmac_f32_e32 v52, v124, v72
	v_fmac_f32_e32 v52, v125, v73
	v_fmac_f32_e32 v52, v126, v74
	v_fmac_f32_e32 v52, v127, v75
	s_waitcnt lgkmcnt(0)
	v_fmac_f32_e32 v52, v128, v76
	v_fmac_f32_e32 v52, v129, v77
	v_fmac_f32_e32 v52, v130, v78
	v_fmac_f32_e32 v52, v131, v79
	v_min_f32_e32 v132, 0, v52
	v_mul_f32_e64 v52, |v52|, s52
	v_exp_f32_e32 v52, v52
	s_nop 0
	v_add_f32_e32 v52, 1.0, v52
	v_log_f32_e32 v52, v52
	s_nop 0
	v_mul_f32_e32 v133, 0x3f317217, v52
	v_fma_f32 v133, v52, s53, -v133
	v_fmac_f32_e32 v133, 0x3377d1cf, v52
	v_fmac_f32_e32 v133, 0x3f317217, v52
	v_sub_f32_e32 v52, v132, v133
	v_mul_f32_e32 v52, 0x3d800000, v52
	ds_read_b128 v[116:119], v12 offset:2688
	ds_read_b128 v[120:123], v12 offset:2704
	ds_read_b128 v[124:127], v12 offset:2720
	ds_read_b128 v[128:131], v12 offset:2736
	v_mov_b32_e32 v53, v80
	s_waitcnt lgkmcnt(3)
	v_fmac_f32_e32 v53, v116, v64
	v_fmac_f32_e32 v53, v117, v65
	v_fmac_f32_e32 v53, v118, v66
	v_fmac_f32_e32 v53, v119, v67
	s_waitcnt lgkmcnt(2)
	v_fmac_f32_e32 v53, v120, v68
	v_fmac_f32_e32 v53, v121, v69
	v_fmac_f32_e32 v53, v122, v70
	v_fmac_f32_e32 v53, v123, v71
	s_waitcnt lgkmcnt(1)
	v_fmac_f32_e32 v53, v124, v72
	v_fmac_f32_e32 v53, v125, v73
	v_fmac_f32_e32 v53, v126, v74
	v_fmac_f32_e32 v53, v127, v75
	s_waitcnt lgkmcnt(0)
	v_fmac_f32_e32 v53, v128, v76
	v_fmac_f32_e32 v53, v129, v77
	v_fmac_f32_e32 v53, v130, v78
	v_fmac_f32_e32 v53, v131, v79
	v_min_f32_e32 v132, 0, v53
	v_mul_f32_e64 v53, |v53|, s52
	v_exp_f32_e32 v53, v53
	s_nop 0
	v_add_f32_e32 v53, 1.0, v53
	v_log_f32_e32 v53, v53
	s_nop 0
	v_mul_f32_e32 v133, 0x3f317217, v53
	v_fma_f32 v133, v53, s53, -v133
	v_fmac_f32_e32 v133, 0x3377d1cf, v53
	v_fmac_f32_e32 v133, 0x3f317217, v53
	v_sub_f32_e32 v53, v132, v133
	v_mul_f32_e32 v53, 0x3d800000, v53
	ds_read_b128 v[116:119], v12 offset:2816
	ds_read_b128 v[120:123], v12 offset:2832
	ds_read_b128 v[124:127], v12 offset:2848
	ds_read_b128 v[128:131], v12 offset:2864
	v_mov_b32_e32 v54, v80
	s_waitcnt lgkmcnt(3)
	v_fmac_f32_e32 v54, v116, v64
	v_fmac_f32_e32 v54, v117, v65
	v_fmac_f32_e32 v54, v118, v66
	v_fmac_f32_e32 v54, v119, v67
	s_waitcnt lgkmcnt(2)
	v_fmac_f32_e32 v54, v120, v68
	v_fmac_f32_e32 v54, v121, v69
	v_fmac_f32_e32 v54, v122, v70
	v_fmac_f32_e32 v54, v123, v71
	s_waitcnt lgkmcnt(1)
	v_fmac_f32_e32 v54, v124, v72
	v_fmac_f32_e32 v54, v125, v73
	v_fmac_f32_e32 v54, v126, v74
	v_fmac_f32_e32 v54, v127, v75
	s_waitcnt lgkmcnt(0)
	v_fmac_f32_e32 v54, v128, v76
	v_fmac_f32_e32 v54, v129, v77
	v_fmac_f32_e32 v54, v130, v78
	v_fmac_f32_e32 v54, v131, v79
	v_min_f32_e32 v132, 0, v54
	v_mul_f32_e64 v54, |v54|, s52
	v_exp_f32_e32 v54, v54
	s_nop 0
	v_add_f32_e32 v54, 1.0, v54
	v_log_f32_e32 v54, v54
	s_nop 0
	v_mul_f32_e32 v133, 0x3f317217, v54
	v_fma_f32 v133, v54, s53, -v133
	v_fmac_f32_e32 v133, 0x3377d1cf, v54
	v_fmac_f32_e32 v133, 0x3f317217, v54
	v_sub_f32_e32 v54, v132, v133
	v_mul_f32_e32 v54, 0x3d800000, v54
	ds_read_b128 v[116:119], v12 offset:2944
	ds_read_b128 v[120:123], v12 offset:2960
	ds_read_b128 v[124:127], v12 offset:2976
	ds_read_b128 v[128:131], v12 offset:2992
	v_mov_b32_e32 v55, v80
	s_waitcnt lgkmcnt(3)
	v_fmac_f32_e32 v55, v116, v64
	v_fmac_f32_e32 v55, v117, v65
	v_fmac_f32_e32 v55, v118, v66
	v_fmac_f32_e32 v55, v119, v67
	s_waitcnt lgkmcnt(2)
	v_fmac_f32_e32 v55, v120, v68
	v_fmac_f32_e32 v55, v121, v69
	v_fmac_f32_e32 v55, v122, v70
	v_fmac_f32_e32 v55, v123, v71
	s_waitcnt lgkmcnt(1)
	v_fmac_f32_e32 v55, v124, v72
	v_fmac_f32_e32 v55, v125, v73
	v_fmac_f32_e32 v55, v126, v74
	v_fmac_f32_e32 v55, v127, v75
	s_waitcnt lgkmcnt(0)
	v_fmac_f32_e32 v55, v128, v76
	v_fmac_f32_e32 v55, v129, v77
	v_fmac_f32_e32 v55, v130, v78
	v_fmac_f32_e32 v55, v131, v79
	v_min_f32_e32 v132, 0, v55
	v_mul_f32_e64 v55, |v55|, s52
	v_exp_f32_e32 v55, v55
	s_nop 0
	v_add_f32_e32 v55, 1.0, v55
	v_log_f32_e32 v55, v55
	s_nop 0
	v_mul_f32_e32 v133, 0x3f317217, v55
	v_fma_f32 v133, v55, s53, -v133
	v_fmac_f32_e32 v133, 0x3377d1cf, v55
	v_fmac_f32_e32 v133, 0x3f317217, v55
	v_sub_f32_e32 v55, v132, v133
	v_mul_f32_e32 v55, 0x3d800000, v55
	ds_read_b128 v[116:119], v12 offset:3072
	ds_read_b128 v[120:123], v12 offset:3088
	ds_read_b128 v[124:127], v12 offset:3104
	ds_read_b128 v[128:131], v12 offset:3120
	v_mov_b32_e32 v56, v80
	s_waitcnt lgkmcnt(3)
	v_fmac_f32_e32 v56, v116, v64
	v_fmac_f32_e32 v56, v117, v65
	v_fmac_f32_e32 v56, v118, v66
	v_fmac_f32_e32 v56, v119, v67
	s_waitcnt lgkmcnt(2)
	v_fmac_f32_e32 v56, v120, v68
	v_fmac_f32_e32 v56, v121, v69
	v_fmac_f32_e32 v56, v122, v70
	v_fmac_f32_e32 v56, v123, v71
	s_waitcnt lgkmcnt(1)
	v_fmac_f32_e32 v56, v124, v72
	v_fmac_f32_e32 v56, v125, v73
	v_fmac_f32_e32 v56, v126, v74
	v_fmac_f32_e32 v56, v127, v75
	s_waitcnt lgkmcnt(0)
	v_fmac_f32_e32 v56, v128, v76
	v_fmac_f32_e32 v56, v129, v77
	v_fmac_f32_e32 v56, v130, v78
	v_fmac_f32_e32 v56, v131, v79
	v_min_f32_e32 v132, 0, v56
	v_mul_f32_e64 v56, |v56|, s52
	v_exp_f32_e32 v56, v56
	s_nop 0
	v_add_f32_e32 v56, 1.0, v56
	v_log_f32_e32 v56, v56
	s_nop 0
	v_mul_f32_e32 v133, 0x3f317217, v56
	v_fma_f32 v133, v56, s53, -v133
	v_fmac_f32_e32 v133, 0x3377d1cf, v56
	v_fmac_f32_e32 v133, 0x3f317217, v56
	v_sub_f32_e32 v56, v132, v133
	v_mul_f32_e32 v56, 0x3d800000, v56
	ds_read_b128 v[116:119], v12 offset:3200
	ds_read_b128 v[120:123], v12 offset:3216
	ds_read_b128 v[124:127], v12 offset:3232
	ds_read_b128 v[128:131], v12 offset:3248
	v_mov_b32_e32 v57, v80
	s_waitcnt lgkmcnt(3)
; DEVINL float logsig(float z) { return fminf(z, 0.f) - __logf(1.f + __expf(-fabsf(z))); }
; DEVINL void gla_prep_unit(const Params& p, int unit) {
;     ...
;     for (int i = 0; i < 64; ++i) {
;       float z = bias;
; #pragma unroll
;       for (int r = 0; r < 16; ++r) z += afab[i * 32 + dir * 16 + r] * u[r];
;       Gc[i * 128] = logsig(z) * (1.f / 16.f);
	v_fmac_f32_e32 v57, v116, v64
	v_fmac_f32_e32 v57, v117, v65
	v_fmac_f32_e32 v57, v118, v66
	v_fmac_f32_e32 v57, v119, v67
	s_waitcnt lgkmcnt(2)
	v_fmac_f32_e32 v57, v120, v68
	v_fmac_f32_e32 v57, v121, v69
	v_fmac_f32_e32 v57, v122, v70
	v_fmac_f32_e32 v57, v123, v71
	s_waitcnt lgkmcnt(1)
	v_fmac_f32_e32 v57, v124, v72
	v_fmac_f32_e32 v57, v125, v73
	v_fmac_f32_e32 v57, v126, v74
	v_fmac_f32_e32 v57, v127, v75
	s_waitcnt lgkmcnt(0)
	v_fmac_f32_e32 v57, v128, v76
	v_fmac_f32_e32 v57, v129, v77
	v_fmac_f32_e32 v57, v130, v78
	v_fmac_f32_e32 v57, v131, v79
	v_min_f32_e32 v132, 0, v57
	v_mul_f32_e64 v57, |v57|, s52
	v_exp_f32_e32 v57, v57
	s_nop 0
	v_add_f32_e32 v57, 1.0, v57
	v_log_f32_e32 v57, v57
	s_nop 0
	v_mul_f32_e32 v133, 0x3f317217, v57
	v_fma_f32 v133, v57, s53, -v133
	v_fmac_f32_e32 v133, 0x3377d1cf, v57
	v_fmac_f32_e32 v133, 0x3f317217, v57
	v_sub_f32_e32 v57, v132, v133
	v_mul_f32_e32 v57, 0x3d800000, v57
	ds_read_b128 v[116:119], v12 offset:3328
	ds_read_b128 v[120:123], v12 offset:3344
	ds_read_b128 v[124:127], v12 offset:3360
	ds_read_b128 v[128:131], v12 offset:3376
	v_mov_b32_e32 v58, v80
	s_waitcnt lgkmcnt(3)
	v_fmac_f32_e32 v58, v116, v64
	v_fmac_f32_e32 v58, v117, v65
	v_fmac_f32_e32 v58, v118, v66
	v_fmac_f32_e32 v58, v119, v67
	s_waitcnt lgkmcnt(2)
	v_fmac_f32_e32 v58, v120, v68
	v_fmac_f32_e32 v58, v121, v69
	v_fmac_f32_e32 v58, v122, v70
	v_fmac_f32_e32 v58, v123, v71
	s_waitcnt lgkmcnt(1)
	v_fmac_f32_e32 v58, v124, v72
	v_fmac_f32_e32 v58, v125, v73
	v_fmac_f32_e32 v58, v126, v74
	v_fmac_f32_e32 v58, v127, v75
	s_waitcnt lgkmcnt(0)
	v_fmac_f32_e32 v58, v128, v76
	v_fmac_f32_e32 v58, v129, v77
	v_fmac_f32_e32 v58, v130, v78
	v_fmac_f32_e32 v58, v131, v79
	v_min_f32_e32 v132, 0, v58
	v_mul_f32_e64 v58, |v58|, s52
	v_exp_f32_e32 v58, v58
	s_nop 0
	v_add_f32_e32 v58, 1.0, v58
	v_log_f32_e32 v58, v58
	s_nop 0
	v_mul_f32_e32 v133, 0x3f317217, v58
	v_fma_f32 v133, v58, s53, -v133
	v_fmac_f32_e32 v133, 0x3377d1cf, v58
	v_fmac_f32_e32 v133, 0x3f317217, v58
	v_sub_f32_e32 v58, v132, v133
	v_mul_f32_e32 v58, 0x3d800000, v58
	ds_read_b128 v[116:119], v12 offset:3456
	ds_read_b128 v[120:123], v12 offset:3472
	ds_read_b128 v[124:127], v12 offset:3488
	ds_read_b128 v[128:131], v12 offset:3504
	v_mov_b32_e32 v59, v80
	s_waitcnt lgkmcnt(3)
	v_fmac_f32_e32 v59, v116, v64
	v_fmac_f32_e32 v59, v117, v65
	v_fmac_f32_e32 v59, v118, v66
	v_fmac_f32_e32 v59, v119, v67
	s_waitcnt lgkmcnt(2)
	v_fmac_f32_e32 v59, v120, v68
	v_fmac_f32_e32 v59, v121, v69
	v_fmac_f32_e32 v59, v122, v70
	v_fmac_f32_e32 v59, v123, v71
	s_waitcnt lgkmcnt(1)
	v_fmac_f32_e32 v59, v124, v72
	v_fmac_f32_e32 v59, v125, v73
	v_fmac_f32_e32 v59, v126, v74
	v_fmac_f32_e32 v59, v127, v75
	s_waitcnt lgkmcnt(0)
	v_fmac_f32_e32 v59, v128, v76
	v_fmac_f32_e32 v59, v129, v77
	v_fmac_f32_e32 v59, v130, v78
	v_fmac_f32_e32 v59, v131, v79
	v_min_f32_e32 v132, 0, v59
	v_mul_f32_e64 v59, |v59|, s52
	v_exp_f32_e32 v59, v59
	s_nop 0
	v_add_f32_e32 v59, 1.0, v59
	v_log_f32_e32 v59, v59
	s_nop 0
	v_mul_f32_e32 v133, 0x3f317217, v59
	v_fma_f32 v133, v59, s53, -v133
	v_fmac_f32_e32 v133, 0x3377d1cf, v59
	v_fmac_f32_e32 v133, 0x3f317217, v59
	v_sub_f32_e32 v59, v132, v133
	v_mul_f32_e32 v59, 0x3d800000, v59
	ds_read_b128 v[116:119], v12 offset:3584
	ds_read_b128 v[120:123], v12 offset:3600
	ds_read_b128 v[124:127], v12 offset:3616
	ds_read_b128 v[128:131], v12 offset:3632
	v_mov_b32_e32 v60, v80
	s_waitcnt lgkmcnt(3)
	v_fmac_f32_e32 v60, v116, v64
	v_fmac_f32_e32 v60, v117, v65
	v_fmac_f32_e32 v60, v118, v66
	v_fmac_f32_e32 v60, v119, v67
	s_waitcnt lgkmcnt(2)
	v_fmac_f32_e32 v60, v120, v68
	v_fmac_f32_e32 v60, v121, v69
	v_fmac_f32_e32 v60, v122, v70
	v_fmac_f32_e32 v60, v123, v71
	s_waitcnt lgkmcnt(1)
	v_fmac_f32_e32 v60, v124, v72
	v_fmac_f32_e32 v60, v125, v73
	v_fmac_f32_e32 v60, v126, v74
	v_fmac_f32_e32 v60, v127, v75
	s_waitcnt lgkmcnt(0)
	v_fmac_f32_e32 v60, v128, v76
	v_fmac_f32_e32 v60, v129, v77
	v_fmac_f32_e32 v60, v130, v78
	v_fmac_f32_e32 v60, v131, v79
	v_min_f32_e32 v132, 0, v60
	v_mul_f32_e64 v60, |v60|, s52
	v_exp_f32_e32 v60, v60
	s_nop 0
	v_add_f32_e32 v60, 1.0, v60
	v_log_f32_e32 v60, v60
	s_nop 0
	v_mul_f32_e32 v133, 0x3f317217, v60
	v_fma_f32 v133, v60, s53, -v133
	v_fmac_f32_e32 v133, 0x3377d1cf, v60
	v_fmac_f32_e32 v133, 0x3f317217, v60
	v_sub_f32_e32 v60, v132, v133
	v_mul_f32_e32 v60, 0x3d800000, v60
	ds_read_b128 v[116:119], v12 offset:3712
	ds_read_b128 v[120:123], v12 offset:3728
	ds_read_b128 v[124:127], v12 offset:3744
	ds_read_b128 v[128:131], v12 offset:3760
	v_mov_b32_e32 v61, v80
	s_waitcnt lgkmcnt(3)
; DEVINL float logsig(float z) { return fminf(z, 0.f) - __logf(1.f + __expf(-fabsf(z))); }
; DEVINL void gla_prep_unit(const Params& p, int unit) {
;     ...
;     for (int i = 0; i < 64; ++i) {
;       float z = bias;
; #pragma unroll
;       for (int r = 0; r < 16; ++r) z += afab[i * 32 + dir * 16 + r] * u[r];
;       Gc[i * 128] = logsig(z) * (1.f / 16.f);
;     }
;     float run = 0.f;
;     if (dir == 0) { for (int i = 0; i < 64; ++i) { run += Gc[i * 128]; Gc[i * 128] = run; } }
;     else { for (int i = 63; i >= 0; --i) { run += Gc[i * 128]; Gc[i * 128] = run; } }
	v_fmac_f32_e32 v61, v116, v64
	v_fmac_f32_e32 v61, v117, v65
	v_fmac_f32_e32 v61, v118, v66
	v_fmac_f32_e32 v61, v119, v67
	s_waitcnt lgkmcnt(2)
	v_fmac_f32_e32 v61, v120, v68
	v_fmac_f32_e32 v61, v121, v69
	v_fmac_f32_e32 v61, v122, v70
	v_fmac_f32_e32 v61, v123, v71
	s_waitcnt lgkmcnt(1)
	v_fmac_f32_e32 v61, v124, v72
	v_fmac_f32_e32 v61, v125, v73
	v_fmac_f32_e32 v61, v126, v74
	v_fmac_f32_e32 v61, v127, v75
	s_waitcnt lgkmcnt(0)
	v_fmac_f32_e32 v61, v128, v76
	v_fmac_f32_e32 v61, v129, v77
	v_fmac_f32_e32 v61, v130, v78
	v_fmac_f32_e32 v61, v131, v79
	v_min_f32_e32 v132, 0, v61
	v_mul_f32_e64 v61, |v61|, s52
	v_exp_f32_e32 v61, v61
	s_nop 0
	v_add_f32_e32 v61, 1.0, v61
	v_log_f32_e32 v61, v61
	s_nop 0
	v_mul_f32_e32 v133, 0x3f317217, v61
	v_fma_f32 v133, v61, s53, -v133
	v_fmac_f32_e32 v133, 0x3377d1cf, v61
	v_fmac_f32_e32 v133, 0x3f317217, v61
	v_sub_f32_e32 v61, v132, v133
	v_mul_f32_e32 v61, 0x3d800000, v61
	ds_read_b128 v[116:119], v12 offset:3840
	ds_read_b128 v[120:123], v12 offset:3856
	ds_read_b128 v[124:127], v12 offset:3872
	ds_read_b128 v[128:131], v12 offset:3888
	v_mov_b32_e32 v62, v80
	s_waitcnt lgkmcnt(3)
	v_fmac_f32_e32 v62, v116, v64
	v_fmac_f32_e32 v62, v117, v65
	v_fmac_f32_e32 v62, v118, v66
	v_fmac_f32_e32 v62, v119, v67
	s_waitcnt lgkmcnt(2)
	v_fmac_f32_e32 v62, v120, v68
	v_fmac_f32_e32 v62, v121, v69
	v_fmac_f32_e32 v62, v122, v70
	v_fmac_f32_e32 v62, v123, v71
	s_waitcnt lgkmcnt(1)
	v_fmac_f32_e32 v62, v124, v72
	v_fmac_f32_e32 v62, v125, v73
	v_fmac_f32_e32 v62, v126, v74
	v_fmac_f32_e32 v62, v127, v75
	s_waitcnt lgkmcnt(0)
	v_fmac_f32_e32 v62, v128, v76
	v_fmac_f32_e32 v62, v129, v77
	v_fmac_f32_e32 v62, v130, v78
	v_fmac_f32_e32 v62, v131, v79
	v_min_f32_e32 v132, 0, v62
	v_mul_f32_e64 v62, |v62|, s52
	v_exp_f32_e32 v62, v62
	s_nop 0
	v_add_f32_e32 v62, 1.0, v62
	v_log_f32_e32 v62, v62
	s_nop 0
	v_mul_f32_e32 v133, 0x3f317217, v62
	v_fma_f32 v133, v62, s53, -v133
	v_fmac_f32_e32 v133, 0x3377d1cf, v62
	v_fmac_f32_e32 v133, 0x3f317217, v62
	v_sub_f32_e32 v62, v132, v133
	v_mul_f32_e32 v62, 0x3d800000, v62
	ds_read_b128 v[116:119], v12 offset:3968
	ds_read_b128 v[120:123], v12 offset:3984
	ds_read_b128 v[124:127], v12 offset:4000
	ds_read_b128 v[128:131], v12 offset:4016
	v_mov_b32_e32 v63, v80
	s_waitcnt lgkmcnt(3)
	v_fmac_f32_e32 v63, v116, v64
	v_fmac_f32_e32 v63, v117, v65
	v_fmac_f32_e32 v63, v118, v66
	v_fmac_f32_e32 v63, v119, v67
	s_waitcnt lgkmcnt(2)
	v_fmac_f32_e32 v63, v120, v68
	v_fmac_f32_e32 v63, v121, v69
	v_fmac_f32_e32 v63, v122, v70
	v_fmac_f32_e32 v63, v123, v71
	s_waitcnt lgkmcnt(1)
	v_fmac_f32_e32 v63, v124, v72
	v_fmac_f32_e32 v63, v125, v73
	v_fmac_f32_e32 v63, v126, v74
	v_fmac_f32_e32 v63, v127, v75
	s_waitcnt lgkmcnt(0)
	v_fmac_f32_e32 v63, v128, v76
	v_fmac_f32_e32 v63, v129, v77
	v_fmac_f32_e32 v63, v130, v78
	v_fmac_f32_e32 v63, v131, v79
	v_min_f32_e32 v132, 0, v63
	v_mul_f32_e64 v63, |v63|, s52
	v_exp_f32_e32 v63, v63
	s_nop 0
	v_add_f32_e32 v63, 1.0, v63
	v_log_f32_e32 v63, v63
	s_nop 0
	v_mul_f32_e32 v133, 0x3f317217, v63
	v_fma_f32 v133, v63, s53, -v133
	v_fmac_f32_e32 v133, 0x3377d1cf, v63
	v_fmac_f32_e32 v133, 0x3f317217, v63
	v_sub_f32_e32 v63, v132, v133
	v_mul_f32_e32 v63, 0x3d800000, v63
	s_cmp_eq_u32 s71, 0
	s_cbranch_scc0 .Lgl_tot_b
	v_mov_b32_e32 v134, v32
	v_add_f32_e32 v134, v134, v33
	v_add_f32_e32 v134, v134, v34
	v_add_f32_e32 v134, v134, v35
	v_add_f32_e32 v134, v134, v36
	v_add_f32_e32 v134, v134, v37
	v_add_f32_e32 v134, v134, v38
	v_add_f32_e32 v134, v134, v39
	v_add_f32_e32 v134, v134, v40
	v_add_f32_e32 v134, v134, v41
	v_add_f32_e32 v134, v134, v42
	v_add_f32_e32 v134, v134, v43
	v_add_f32_e32 v134, v134, v44
	v_add_f32_e32 v134, v134, v45
	v_add_f32_e32 v134, v134, v46
	v_add_f32_e32 v134, v134, v47
	v_add_f32_e32 v134, v134, v48
	v_add_f32_e32 v134, v134, v49
	v_add_f32_e32 v134, v134, v50
	v_add_f32_e32 v134, v134, v51
	v_add_f32_e32 v134, v134, v52
	v_add_f32_e32 v134, v134, v53
	v_add_f32_e32 v134, v134, v54
	v_add_f32_e32 v134, v134, v55
	v_add_f32_e32 v134, v134, v56
	v_add_f32_e32 v134, v134, v57
	v_add_f32_e32 v134, v134, v58
	v_add_f32_e32 v134, v134, v59
	v_add_f32_e32 v134, v134, v60
	v_add_f32_e32 v134, v134, v61
	v_add_f32_e32 v134, v134, v62
	v_add_f32_e32 v134, v134, v63
	s_branch .Lgl_tot_e
